# v23 + static s_setprio 1 for waves 4-7 in the P4a chunk-operator loop and the P4c item loop
# speedup vs baseline: 1.0013x; 1.0013x over previous
; #define THREAD_IDS() const int lane = pg8::lane_id_fresh(); const int tid = wave * 64 + lane; const int gw = blockIdx.x * 8 + wave; const int gt = blockIdx.x * 512 + tid; (void)gw; (void)gt; (void)tid; (void)lane
; __device__ __forceinline__ void chunk_load(const PAArgs& A, int item, int wave, int lane, ChunkRaw& R) {
;     const bf16* Rr = (const bf16*)(A.ws + WS_R); const bf16* Kr = (const bf16*)(A.ws + WS_K); const bf16* Vr = (const bf16*)(A.ws + WS_V);
;     const bf16* AH = (const bf16*)(A.ws + WS_HBUF + 32 * MiB); const float* LW = (const float*)(A.ws + WS_LW);
;     const int bh = item >> 6, ck = item & 63;
; #pragma unroll
;     for (int i = 0; i < 8; ++i) {
;         const size_t o = ((size_t)bh * SEQ + ck * 64 + wave * 8 + i) * 64 + lane;
;         R.lwv[i] = LW[o]; R.rb[i] = Rr[o]; R.kb[i] = Kr[o]; R.vb[i] = Vr[o]; R.ab[i] = AH[o];
;     }
; }
; __global__ void __launch_bounds__(512, 2) mega_fwd(Args a) {
;     ...
;     for (int rep = 0; rep < REP_P4A; ++rep) {
;         THREAD_IDS();
;         PAArgs p{(const float*)a.in[14], (const float*)a.in[15], ws, (unsigned char*)a.out};
;         ChunkRaw raw; chunk_load(p, blockIdx.x, wave, lane, raw);
;         for (int it = blockIdx.x; it < 4096; it += G) {
;             const ChunkRaw cur = raw;
;             { const int nx = (it + G < 4096) ? it + G : it; chunk_load(p, nx, wave, lane, raw); }
.LBB0_426:
	s_or_b64 exec, exec, s[0:1]
	s_add_u32 s70, s28, 0x15800000
	s_addc_u32 s71, s29, 0
	s_add_u32 s74, s28, 0x17800000
	v_readlane_b32 s0, v242, 0
	s_addc_u32 s75, s29, 0
	s_lshr_b32 s1, s0, 7
	v_readlane_b32 s0, v242, 17
	s_lshl_b32 s0, s0, 1
	s_and_b32 s2, s0, 2
	s_or_b32 s0, s2, 1
	v_writelane_b32 v240, s0, 1
	v_writelane_b32 v240, s1, 2
	s_lshl_b32 s0, s1, 10
	v_writelane_b32 v240, s0, 3
	s_lshl_b32 s0, s2, 8
	v_writelane_b32 v240, s2, 4
	s_cmpk_gt_i32 s88, 0xfff
	s_waitcnt lgkmcnt(0)
	s_barrier
	v_writelane_b32 v240, s0, 5
	v_mbcnt_lo_u32_b32 v8, -1, 0
	v_mbcnt_hi_u32_b32 v8, -1, v8
	s_cbranch_scc1 .LBB0_437
	v_readlane_b32 s5, v242, 17
	s_lshl_b32 s35, s5, 3
	v_readlane_b32 s15, v242, 0
	s_cmp_lt_u32 s15, 64
	s_cselect_b64 s[38:39], -1, 0
	s_cmpk_gt_u32 s15, 0x7f
	s_cselect_b64 s[0:1], -1, 0
	v_writelane_b32 v241, s0, 61
	s_cmpk_gt_u32 s15, 0xbf
	v_ashrrev_i32_e32 v9, 31, v8
	v_writelane_b32 v241, s1, 62
	s_cselect_b64 s[0:1], -1, 0
	v_writelane_b32 v241, s0, 63
	s_cmpk_gt_u32 s15, 0xff
	v_readlane_b32 s36, v241, 51
	v_writelane_b32 v240, s1, 0
	s_cselect_b64 s[0:1], -1, 0
	v_writelane_b32 v240, s0, 6
	s_cmpk_gt_u32 s15, 0x13f
	v_readlane_b32 s8, v241, 28
	v_writelane_b32 v240, s1, 7
	s_cselect_b64 s[0:1], -1, 0
	v_writelane_b32 v240, s0, 8
	s_cmpk_gt_u32 s15, 0x17f
	v_readlane_b32 s9, v241, 29
	v_writelane_b32 v240, s1, 9
	s_cselect_b64 s[0:1], -1, 0
	v_writelane_b32 v240, s0, 10
	s_cmpk_gt_u32 s15, 0x1bf
	v_and_b32_e32 v90, 15, v8
	v_writelane_b32 v240, s1, 11
	s_cselect_b64 s[0:1], -1, 0
	v_writelane_b32 v240, s0, 12
	s_cmpk_gt_u32 s15, 0x1ff
	v_cmp_eq_u32_e32 vcc, 0, v90
	v_writelane_b32 v240, s1, 13
	s_cselect_b64 s[0:1], -1, 0
	v_writelane_b32 v240, s0, 14
	v_readlane_b32 s37, v241, 52
	v_and_b32_e32 v93, -16, v8
	v_writelane_b32 v240, s1, 15
	v_lshlrev_b32_e32 v113, 3, v90
	v_readlane_b32 s6, v240, 2
	v_readlane_b32 s14, v240, 4
	s_cmp_eq_u32 s14, s6
	s_cselect_b64 s[0:1], -1, 0
	v_writelane_b32 v240, s0, 16
	v_lshl_or_b32 v99, s14, 4, v90
	v_and_b32_e32 v109, 0x1ffffff0, v8
	v_writelane_b32 v240, s1, 17
	v_or_b32_e32 v110, 15, v8
	v_readlane_b32 s0, v240, 1
	s_cmp_eq_u32 s0, s6
	s_cselect_b64 s[0:1], -1, 0
	s_add_u32 s42, s28, 0x11800000
	s_addc_u32 s43, s29, 0
	s_add_u32 s44, s28, 0x13800000
	s_addc_u32 s45, s29, 0
	v_writelane_b32 v240, s0, 18
	s_add_u32 s46, s28, 0x4800000
	s_addc_u32 s47, s29, 0
	v_writelane_b32 v240, s1, 19
	s_ashr_i32 s0, s36, 6
	s_ashr_i32 s1, s0, 31
	s_lshl_b32 s2, s36, 6
	s_lshl_b64 s[0:1], s[0:1], 12
	s_and_b32 s2, s2, 0xfc0
	s_or_b32 s0, s0, s2
	s_add_u32 s0, s0, s35
	s_addc_u32 s1, s1, 0
	s_lshl_b64 s[0:1], s[0:1], 6
	v_lshl_add_u64 v[0:1], s[0:1], 0, v[8:9]
	s_mov_b64 s[0:1], 0x1c0
	v_lshl_add_u64 v[2:3], v[0:1], 0, s[0:1]
	s_mov_b64 s[0:1], 0x180
	v_lshlrev_b64 v[4:5], 1, v[2:3]
	v_lshl_add_u64 v[18:19], v[0:1], 0, s[0:1]
	v_lshl_add_u64 v[6:7], s[46:47], 0, v[4:5]
	v_lshl_add_u64 v[12:13], s[44:45], 0, v[4:5]
	v_lshlrev_b64 v[20:21], 1, v[18:19]
	s_mov_b64 s[0:1], 0x140
	v_lshl_add_u64 v[10:11], s[70:71], 0, v[4:5]
	v_lshl_add_u64 v[14:15], s[42:43], 0, v[4:5]
	v_lshl_add_u64 v[16:17], v[2:3], 2, s[74:75]
	v_lshl_add_u64 v[22:23], s[46:47], 0, v[20:21]
	v_lshl_add_u64 v[24:25], s[70:71], 0, v[20:21]
	v_lshl_add_u64 v[26:27], s[44:45], 0, v[20:21]
	global_load_ushort v2, v[6:7], off
	global_load_ushort v29, v[10:11], off
	global_load_ushort v4, v[12:13], off
	global_load_ushort v37, v[14:15], off
	global_load_dword v43, v[16:17], off
	global_load_ushort v3, v[22:23], off
	global_load_ushort v30, v[24:25], off
	global_load_ushort v5, v[26:27], off
	v_lshl_add_u64 v[12:13], v[0:1], 0, s[0:1]
	s_mov_b64 s[0:1], 0x100
	v_lshlrev_b64 v[14:15], 1, v[12:13]
	v_lshl_add_u64 v[22:23], v[0:1], 0, s[0:1]
	v_lshl_add_u64 v[6:7], s[42:43], 0, v[20:21]
	v_lshl_add_u64 v[20:21], s[44:45], 0, v[14:15]
	v_lshl_add_u64 v[12:13], v[12:13], 2, s[74:75]
	v_lshlrev_b64 v[24:25], 1, v[22:23]
	s_mov_b64 s[0:1], 0xc0
	v_lshl_add_u64 v[10:11], v[18:19], 2, s[74:75]
	v_lshl_add_u64 v[16:17], s[46:47], 0, v[14:15]
	v_lshl_add_u64 v[18:19], s[70:71], 0, v[14:15]
	v_lshl_add_u64 v[14:15], s[42:43], 0, v[14:15]
	v_lshl_add_u64 v[26:27], s[46:47], 0, v[24:25]
	global_load_ushort v40, v[6:7], off
	global_load_dword v44, v[10:11], off
	s_nop 0
	global_load_ushort v6, v[16:17], off
	global_load_ushort v34, v[18:19], off
	global_load_ushort v7, v[20:21], off
	global_load_ushort v41, v[14:15], off
	global_load_dword v45, v[12:13], off
	s_nop 0
	global_load_ushort v12, v[26:27], off
	v_lshl_add_u64 v[20:21], v[0:1], 0, s[0:1]
	v_lshl_add_u64 v[10:11], s[70:71], 0, v[24:25]
	v_lshl_add_u64 v[14:15], s[44:45], 0, v[24:25]
	v_lshl_add_u64 v[16:17], s[42:43], 0, v[24:25]
	v_lshl_add_u64 v[18:19], v[22:23], 2, s[74:75]
	v_lshlrev_b64 v[22:23], 1, v[20:21]
	s_mov_b64 s[0:1], 0x80
	v_lshl_add_u64 v[24:25], s[46:47], 0, v[22:23]
	v_lshl_add_u64 v[32:33], s[70:71], 0, v[22:23]
	v_lshl_add_u64 v[38:39], s[44:45], 0, v[22:23]
	v_lshl_add_u64 v[22:23], s[42:43], 0, v[22:23]
	global_load_ushort v27, v[10:11], off
	global_load_ushort v13, v[14:15], off
	global_load_ushort v35, v[16:17], off
	global_load_dword v42, v[18:19], off
	s_nop 0
	global_load_ushort v14, v[24:25], off
	global_load_ushort v28, v[32:33], off
	global_load_ushort v15, v[38:39], off
	global_load_ushort v36, v[22:23], off
	v_lshl_add_u64 v[16:17], v[0:1], 0, s[0:1]
	v_lshlrev_b64 v[18:19], 1, v[16:17]
	v_lshl_add_u64 v[48:49], v[0:1], 0, 64
	v_lshl_add_u64 v[10:11], v[20:21], 2, s[74:75]
	v_lshl_add_u64 v[20:21], s[46:47], 0, v[18:19]
	v_lshl_add_u64 v[22:23], s[70:71], 0, v[18:19]
	v_lshl_add_u64 v[32:33], s[44:45], 0, v[18:19]
	v_lshl_add_u64 v[18:19], s[42:43], 0, v[18:19]
; __device__ __forceinline__ void chunk_load(const PAArgs& A, int item, int wave, int lane, ChunkRaw& R) {
;     ...
;     const int bh = item >> 6, ck = item & 63;
; #pragma unroll
;     for (int i = 0; i < 8; ++i) {
;         const size_t o = ((size_t)bh * SEQ + ck * 64 + wave * 8 + i) * 64 + lane;
;         R.lwv[i] = LW[o]; R.rb[i] = Rr[o]; R.kb[i] = Kr[o]; R.vb[i] = Vr[o]; R.ab[i] = AH[o];
;     }
; }
; __device__ __forceinline__ void chunk_item(const PAArgs& A, unsigned char* lds, int item, int tid, int wave, int lane, const ChunkRaw& RAW) {
;     ...
;     const int bh = item >> 6, ck = item & 63, b = bh >> 3, h = bh & 7;
;     const size_t tok0 = (size_t)b * SEQ + ck * 64;
;     const int fr = lane & 15, fq = lane >> 4;
;     LBAR();
;     {
;         const int ch = lane, tg = wave;
;         float lwv[8], rv[8], kv[8], av[8], pl[8]; bf16 vb[8];
;         float run = 0.f;
; #pragma unroll
;         for (int i = 0; i < 8; ++i) {
;             lwv[i] = RAW.lwv[i]; rv[i] = bf2f(RAW.rb[i]); kv[i] = bf2f(RAW.kb[i]); vb[i] = RAW.vb[i]; av[i] = bf2f(RAW.ab[i]);
;             run += lwv[i]; pl[i] = run;
;         }
;         CUMT[tg * 64 + ch] = run;
;         LBAR();
;         float off = 0.f, tot = 0.f;
; #pragma unroll
;         for (int g = 0; g < 8; ++g) { const float c = CUMT[g * 64 + ch]; tot += c; off += (g < tg) ? c : 0.f; }
;         const float kkc = A.k_k[h * 64 + ch], kac = A.k_a[h * 64 + ch];
;         const float etot = __expf(tot);
;         unsigned bhp[4], khp[4], vp[4];
;         float bhv[8], khv[8], atv[8];
; #pragma unroll
;         for (int i = 0; i < 8; ++i) {
;             const float cl = off + pl[i], clp = cl - lwv[i];
;             const float kq = kv[i] * kkc;
;             const float kk = kq * __builtin_amdgcn_rsqf(fmaxf(wave_sum(kq * kq), 1e-24f));
;             const float a_ = -kk, b_ = kk * av[i], kp = kv[i] * (1.0f + (av[i] - 1.0f) * kac);
;             const float ecl = __expf(cl), encl = __builtin_amdgcn_rcpf(ecl), eclp = __expf(clp), eh = etot * encl;
;             const int tok = tg * 8 + i;
;             atv[i] = a_ * eclp; AT[tok * MST + ch] = (bf16)f2bf(a_ * eclp); BT[tok * MST + ch] = (bf16)f2bf(b_ * encl); KT[tok * MST + ch] = (bf16)f2bf(kp * encl); RT[tok * MST + ch] = (bf16)f2bf(rv[i] * ecl);
;             bhv[i] = b_ * eh; khv[i] = kp * eh;
;         }
; #pragma unroll
	v_lshlrev_b64 v[50:51], 1, v[48:49]
	v_lshl_add_u64 v[46:47], v[16:17], 2, s[74:75]
	v_lshl_add_u64 v[52:53], s[46:47], 0, v[50:51]
	v_lshl_add_u64 v[54:55], s[70:71], 0, v[50:51]
	global_load_dword v38, v[10:11], off
	global_load_ushort v16, v[20:21], off
	global_load_ushort v24, v[22:23], off
	global_load_ushort v17, v[32:33], off
	s_nop 0
	global_load_ushort v32, v[18:19], off
	global_load_dword v39, v[46:47], off
	s_nop 0
	global_load_ushort v18, v[52:53], off
	global_load_ushort v26, v[54:55], off
	v_lshl_add_u64 v[10:11], s[44:45], 0, v[50:51]
	v_lshl_add_u64 v[20:21], s[42:43], 0, v[50:51]
	v_lshlrev_b64 v[22:23], 1, v[0:1]
	v_lshl_add_u64 v[46:47], v[48:49], 2, s[74:75]
	v_lshl_add_u64 v[48:49], s[46:47], 0, v[22:23]
	v_lshl_add_u64 v[50:51], s[70:71], 0, v[22:23]
	v_lshl_add_u64 v[52:53], s[44:45], 0, v[22:23]
	v_lshl_add_u64 v[54:55], s[42:43], 0, v[22:23]
	v_lshl_add_u64 v[0:1], v[0:1], 2, s[74:75]
	global_load_ushort v19, v[10:11], off
	global_load_ushort v23, v[20:21], off
	global_load_dword v31, v[46:47], off
	s_nop 0
	global_load_ushort v20, v[48:49], off
	global_load_ushort v22, v[50:51], off
	global_load_ushort v21, v[52:53], off
	global_load_ushort v25, v[54:55], off
	global_load_dword v33, v[0:1], off
	s_add_i32 s2, 0, 0x18c00
	s_add_i32 s3, 0, 0x16800
	s_and_b64 s[0:1], s[8:9], exec
	s_cselect_b32 s7, s3, s2
	s_add_i32 s12, 0, 0x1d400
	s_add_i32 s4, 0, 0x1b000
	s_and_b64 s[0:1], s[8:9], exec
	s_mul_i32 s1, s5, 0x240
	v_cndmask_b32_e64 v54, 0, 1.0, vcc
	v_cmp_eq_u32_e32 vcc, 1, v90
	v_add_u32_e32 v1, s1, v8
	v_readlane_b32 s9, v241, 50
	v_cndmask_b32_e64 v55, 0, 1.0, vcc
	v_cmp_eq_u32_e32 vcc, 2, v90
	v_lshl_add_u32 v48, v1, 1, 0
	v_ashrrev_i32_e32 v1, 4, v8
	s_movk_i32 s1, 0x90
	v_cndmask_b32_e64 v59, 0, 1.0, vcc
	v_cmp_eq_u32_e32 vcc, 3, v90
	s_cselect_b32 s10, s4, s12
	s_lshl_b32 s0, s6, 4
	s_add_i32 s4, s4, s9
	s_add_i32 s8, s9, 0
	v_mul_lo_u32 v10, v8, s1
	v_lshlrev_b32_e32 v91, 2, v1
	v_cndmask_b32_e64 v60, 0, 1.0, vcc
	v_cmp_eq_u32_e32 vcc, 4, v90
	v_add_u32_e32 v49, s8, v10
	v_add_u32_e32 v50, s4, v10
	v_or_b32_e32 v10, s0, v90
	v_add_u32_e32 v101, s0, v91
	s_lshl_b32 s0, s15, 6
	v_cndmask_b32_e64 v61, 0, 1.0, vcc
	v_cmp_eq_u32_e32 vcc, 5, v90
	s_and_b32 s16, s0, 0x1000
	s_lshl_b32 s0, s15, 1
	v_cndmask_b32_e64 v62, 0, 1.0, vcc
	v_cmp_eq_u32_e32 vcc, 6, v90
	v_mul_lo_u32 v92, v10, s1
	s_and_b32 s15, s0, 0xffffff00
	v_readlane_b32 s0, v240, 3
	v_readlane_b32 s1, v240, 5
	v_cndmask_b32_e64 v63, 0, 1.0, vcc
	v_cmp_eq_u32_e32 vcc, 7, v90
	s_lshl_b32 s5, s5, 8
	s_add_i32 s13, 0, 0x21c00
	s_add_i32 s0, s0, s1
	v_cndmask_b32_e64 v64, 0, 1.0, vcc
	v_cmp_eq_u32_e32 vcc, 8, v90
	s_lshl_b32 s6, s6, 5
	s_add_i32 s5, s13, s5
	v_lshlrev_b32_e32 v0, 2, v8
	s_ashr_i32 s1, s0, 31
	v_lshlrev_b32_e32 v10, 6, v10
	v_cndmask_b32_e64 v65, 0, 1.0, vcc
	v_cmp_eq_u32_e32 vcc, 9, v90
	s_add_i32 s12, s12, s6
	v_add_u32_e32 v46, s5, v0
	s_add_i32 s11, 0, 0x23600
	s_add_i32 s14, 0, 0x1f800
	s_add_i32 s18, 0, 0x12000
	s_add_i32 s19, 0, 0x14400
	s_add_i32 s17, 0, 0x22c00
	s_lshl_b64 s[50:51], s[36:37], 13
	s_lshl_b64 s[52:53], s[30:31], 13
	s_lshl_b64 s[4:5], s[36:37], 14
	s_lshl_b64 s[20:21], s[0:1], 2
	v_add3_u32 v56, s13, v10, v93
	v_lshlrev_b32_e32 v10, 6, v8
	v_cndmask_b32_e64 v66, 0, 1.0, vcc
	v_cmp_eq_u32_e32 vcc, 10, v90
	v_mul_u32_u24_e32 v11, 0x48, v99
	s_add_u32 s20, s26, s20
	v_and_b32_e32 v10, 0xfffffc00, v10
	v_cndmask_b32_e64 v67, 0, 1.0, vcc
	v_cmp_eq_u32_e32 vcc, 11, v90
	s_mov_b32 s37, 0x5040100
	v_lshlrev_b32_e32 v94, 1, v11
	s_addc_u32 s21, s27, s21
	v_add_u32_e32 v58, s13, v10
	v_cndmask_b32_e64 v68, 0, 1.0, vcc
	v_cmp_eq_u32_e32 vcc, 12, v90
	v_and_or_b32 v10, s9, 48, v90
	s_waitcnt vmcnt(34)
	v_perm_b32 v3, v2, v3, s37
	v_and_b32_e32 v2, 0xffffff80, v0
	s_add_u32 s4, s20, s4
	v_add_u32_e32 v95, 0x900, v94
	v_cndmask_b32_e64 v69, 0, 1.0, vcc
	v_cmp_eq_u32_e32 vcc, 13, v90
	v_mul_u32_u24_e32 v10, 0x48, v10
	v_and_b32_e32 v114, 4, v91
	v_add_u32_e32 v2, s15, v2
	v_lshlrev_b32_e32 v1, 3, v1
	v_add_u32_e32 v11, 0, v94
	s_addc_u32 s5, s21, s5
	v_add_u32_e32 v88, s18, v94
	v_add_u32_e32 v89, s18, v95
	v_add_u32_e32 v96, s19, v94
	v_add_u32_e32 v97, s19, v95
	v_cndmask_b32_e64 v70, 0, 1.0, vcc
	v_cmp_eq_u32_e32 vcc, 14, v90
	v_lshlrev_b32_e32 v86, 1, v101
	v_lshlrev_b32_e32 v10, 1, v10
	v_add_u32_e32 v107, s2, v93
	s_lshl_b64 s[24:25], s[30:31], 14
	s_lshl_b64 s[0:1], s[0:1], 1
	s_waitcnt vmcnt(24)
	v_perm_b32 v122, v6, v12, s37
	v_or3_b32 v12, v2, v113, v114
	v_add3_u32 v52, 0, v92, v93
	v_add3_u32 v57, s12, v94, v1
	v_cndmask_b32_e64 v71, 0, 1.0, vcc
	v_cmp_eq_u32_e32 vcc, 15, v90
	v_add3_u32 v73, s14, v94, v86
	v_add3_u32 v74, s14, v95, v86
	v_add3_u32 v75, s10, v10, v1
	v_add_u32_e32 v98, s14, v1
	v_lshl_add_u32 v105, v90, 1, s17
	v_add_u32_e32 v106, s17, v1
	v_add3_u32 v76, s7, v10, v1
	v_add_u32_e32 v77, v11, v86
	v_add3_u32 v78, 0, v95, v86
	v_add3_u32 v79, v11, s6, v1
	v_add3_u32 v80, s3, v92, v93
	v_ashrrev_i32_e32 v1, 31, v0
	s_add_u32 s0, s26, s0
	v_add_u32_e32 v83, v88, v86
	v_add_u32_e32 v84, v89, v86
	v_add_u32_e32 v85, v96, v86
	v_add_u32_e32 v86, v97, v86
	v_mul_u32_u24_e32 v111, 40, v90
	v_or_b32_e32 v112, 16, v90
	v_add_u32_e32 v90, v107, v92
	v_add_u32_e32 v91, v96, v93
	v_add_u32_e32 v92, v97, v93
	v_mov_b32_e32 v96, s16
	s_waitcnt vmcnt(22)
	v_perm_b32 v123, v7, v13, s37
	v_mov_b32_e32 v97, 0
	v_ashrrev_i32_e32 v13, 31, v12
	v_or_b32_e32 v100, 16, v99
	v_add_u32_e32 v53, v11, v93
	v_or_b32_e32 v102, 1, v101
	v_or_b32_e32 v103, 3, v101
	v_or_b32_e32 v104, 2, v101
	v_lshl_add_u64 v[10:11], v[0:1], 2, s[4:5]
	s_mov_b64 s[2:3], 0x400
	s_addc_u32 s1, s27, s1
	v_add_u32_e32 v108, 17, v99
	v_mul_lo_u32 v109, v109, 40
	v_mul_lo_u32 v110, v110, 40
	v_mul_u32_u24_e32 v112, 0x90, v112
	s_waitcnt vmcnt(14)
; __device__ __forceinline__ void chunk_item(const PAArgs& A, unsigned char* lds, int item, int tid, int wave, int lane, const ChunkRaw& RAW) {
;     ...
;         mm2(BT, AT, ti, tj0, fr, fq, c0, c1);
;         { const f32x4 m0 = S3_MASK(c0, ta, 0), m1 = S3_MASK(c1, tb, 0);
;           *(u32x2*)(AABb + ta * MST + jb) = (u32x2){pk2(m0[0], m0[1]), pk2(m0[2], m0[3])}; *(u32x2*)(AABb + tb * MST + jb) = (u32x2){pk2(m1[0], m1[1]), pk2(m1[2], m1[3])};
;           if (tj0 == ti) *(f32x4*)(Dg + (ti * 16 + fr) * 16 + fq * 4) = m0;
;           if (tj0 + 1 == ti) *(f32x4*)(Dg + (ti * 16 + fr) * 16 + fq * 4) = m1; }
;         c0 = z4; c1 = z4; mm2(KT, AT, ti, tj0, fr, fq, c0, c1);
;         { const f32x4 m0 = S3_MASK(c0, ta, 0), m1 = S3_MASK(c1, tb, 0);
;           *(u32x2*)(AAK + ta * MST + jb) = (u32x2){pk2(m0[0], m0[1]), pk2(m0[2], m0[3])}; *(u32x2*)(AAK + tb * MST + jb) = (u32x2){pk2(m1[0], m1[1]), pk2(m1[2], m1[3])}; }
;         c0 = z4; c1 = z4; mm2(BT, RT, ti, tj0, fr, fq, c0, c1);
;         { const f32x4 m0 = S3_MASK(c0, ta, 1), m1 = S3_MASK(c1, tb, 1);
;           *(u32x2*)(ARB + ta * MST + jb) = (u32x2){pk2(m0[0], m0[1]), pk2(m0[2], m0[3])}; *(u32x2*)(ARB + tb * MST + jb) = (u32x2){pk2(m1[0], m1[1]), pk2(m1[2], m1[3])}; }
;         c0 = z4; c1 = z4; mm2(KT, RT, ti, tj0, fr, fq, c0, c1);
;         { const f32x4 m0 = S3_MASK(c0, ta, 1), m1 = S3_MASK(c1, tb, 1);
;           *(u32x2*)(ARK + ta * MST + jb) = (u32x2){pk2(m0[0], m0[1]), pk2(m0[2], m0[3])}; *(u32x2*)(ARK + tb * MST + jb) = (u32x2){pk2(m1[0], m1[1]), pk2(m1[2], m1[3])}; }
;     ...
;     {
;         typedef short s16x4 __attribute__((ext_vector_type(4)));
;         const int cb = (wave & 3) * 16 + fr;
;         const bf16* src = (wave < 4 ? ATT : AVT) + cb * MST;
;         bf16* dst = (wave < 4 ? X1T : ZT) + cb * MST;
;         s16x4 xb[4];
; #pragma unroll
;         for (int bi = 0; bi < 4; ++bi) {
;             f32x4 acc = bf4(*(const u32x2*)(src + bi * 16 + fq * 4));
; #pragma unroll
;             for (int bj = 0; bj < bi; ++bj) acc = __builtin_amdgcn_mfma_f32_16x16x16bf16_1k(*(const s16x4*)(AABb + (bi * 16 + fr) * MST + bj * 16 + fq * 4), xb[bj], acc, 0, 0, 0);
;             const u32x2 tb = (u32x2){pk2(acc[0], acc[1]), pk2(acc[2], acc[3])};
;             const f32x4 xv = __builtin_amdgcn_mfma_f32_16x16x16bf16_1k(*(const s16x4*)(Tinv + (bi * 16 + fr) * TST + fq * 4), __builtin_bit_cast(s16x4, tb), z4, 0, 0, 0);
	v_perm_b32 v126, v14, v16, s37
	s_waitcnt vmcnt(12)
	v_perm_b32 v127, v15, v17, s37
	v_lshl_add_u64 v[16:17], v[12:13], 1, v[96:97]
	s_mov_b32 s49, 0
	s_mov_b64 s[68:69], 0x80
	v_add_u32_e32 v47, s13, v0
	v_add_u32_e32 v51, s11, v0
	v_cmp_lt_i32_e64 s[54:55], v101, v99
	v_cmp_lt_i32_e64 s[22:23], v102, v99
	v_cmp_lt_i32_e64 s[20:21], v104, v99
	v_cmp_lt_i32_e64 s[56:57], v103, v99
	v_cmp_lt_i32_e64 s[58:59], v101, v100
	v_cndmask_b32_e64 v72, 0, 1.0, vcc
	v_cmp_lt_i32_e64 s[60:61], v102, v100
	v_cmp_lt_i32_e64 s[62:63], v104, v100
	v_cmp_lt_i32_e64 s[64:65], v103, v100
	v_cmp_gt_i32_e64 s[66:67], v101, v99
	v_lshl_add_u32 v81, v99, 2, s11
	v_lshl_add_u32 v82, v100, 2, s11
	v_lshl_add_u64 v[10:11], v[10:11], 0, s[2:3]
	v_cmp_gt_i32_e64 s[72:73], v104, v99
	v_cvt_pk_bf16_f32 v87, v54, s0
	v_add_u32_e32 v88, v88, v93
	v_add_u32_e32 v89, v89, v93
	v_add_u32_e32 v93, v107, v94
	v_add_u32_e32 v94, v107, v95
	v_perm_b32 v5, v4, v5, s37
	s_waitcnt vmcnt(4)
	v_perm_b32 v6, v18, v20, s37
	s_waitcnt vmcnt(2)
	v_perm_b32 v7, v19, v21, s37
	v_lshl_add_u64 v[12:13], s[28:29], 0, v[16:17]
	v_lshl_add_u64 v[14:15], v[0:1], 1, s[0:1]
	v_lshl_add_u64 v[16:17], s[26:27], 0, v[16:17]
	v_add_u32_e32 v95, v105, v109
	v_add_u32_e32 v96, v105, v110
	v_add_u32_e32 v97, v106, v111
	v_add_u32_e32 v98, v98, v112
	v_cmp_gt_i32_e64 s[16:17], v103, v99
	v_cmp_lt_i32_e64 s[76:77], v101, v108
	v_cmp_lt_i32_e64 s[78:79], v102, v108
	v_cmp_lt_i32_e64 s[80:81], v104, v108
	v_cmp_lt_i32_e64 s[82:83], v103, v108
	v_cmp_eq_u32_e64 s[84:85], v101, v99
	v_cmp_eq_u32_e64 s[86:87], v102, v99
	v_cmp_eq_u32_e64 s[88:89], v101, v100
	v_cmp_eq_u32_e64 s[90:91], v102, v100
	v_cmp_eq_u32_e64 s[92:93], v103, v99
	v_cmp_eq_u32_e64 s[94:95], v104, v99
	v_cmp_eq_u32_e64 s[96:97], v103, v100
	v_cmp_eq_u32_e64 s[18:19], v104, v100
	v_readlane_b32 s98, v242, 17
	s_cmp_lt_u32 s98, 4
	s_cbranch_scc1 .Lp4a_noprio
	s_setprio 1
.Lp4a_noprio:
	s_branch .LBB0_429
.LBB0_428:
	s_waitcnt lgkmcnt(0)
	s_barrier
	ds_read_b64 v[0:1], v75
	v_add_u32_e32 v18, 0x800, v98
	s_mov_b32 s6, 0x6000000
	s_waitcnt lgkmcnt(0)
	v_lshlrev_b32_e32 v2, 16, v0
	v_and_b32_e32 v0, 0xffff0000, v0
	v_lshlrev_b32_e32 v3, 16, v1
	v_and_b32_e32 v1, 0xffff0000, v1
	v_cvt_pk_bf16_f32 v0, v2, v0
	v_cvt_pk_bf16_f32 v1, v3, v1
	ds_read_b64 v[2:3], v97
	s_waitcnt lgkmcnt(0)
	v_mfma_f32_16x16x16_bf16 v[0:3], v[2:3], v[0:1], 0
	s_nop 7
	v_cvt_pk_bf16_f32 v0, v0, v1
	v_cvt_pk_bf16_f32 v1, v2, v3
	ds_write_b64 v76, v[0:1]
	ds_read_b64 v[6:7], v98
	ds_read_b64 v[4:5], v75 offset:32
	s_waitcnt lgkmcnt(0)
	v_lshlrev_b32_e32 v2, 16, v4
	v_and_b32_e32 v3, 0xffff0000, v4
	v_lshlrev_b32_e32 v4, 16, v5
	v_and_b32_e32 v5, 0xffff0000, v5
	s_nop 1
	v_mfma_f32_16x16x16_bf16 v[2:5], v[6:7], v[0:1], v[2:5]
	s_nop 7
	v_cvt_pk_bf16_f32 v2, v2, v3
	v_cvt_pk_bf16_f32 v3, v4, v5
	ds_read_b64 v[4:5], v97 offset:640
	s_waitcnt lgkmcnt(0)
	v_mfma_f32_16x16x16_bf16 v[2:5], v[4:5], v[2:3], 0
	s_nop 7
	v_cvt_pk_bf16_f32 v6, v2, v3
	v_cvt_pk_bf16_f32 v7, v4, v5
	ds_write_b64 v76, v[6:7] offset:32
	ds_read2_b64 v[18:21], v18 offset0:32 offset1:36
	ds_read_b64 v[4:5], v75 offset:64
	s_waitcnt lgkmcnt(0)
	v_lshlrev_b32_e32 v2, 16, v4
	v_and_b32_e32 v3, 0xffff0000, v4
	v_lshlrev_b32_e32 v4, 16, v5
	v_and_b32_e32 v5, 0xffff0000, v5
	s_nop 1
	v_mfma_f32_16x16x16_bf16 v[2:5], v[18:19], v[0:1], v[2:5]
	v_add_u32_e32 v18, 0x1000, v98
	v_mfma_f32_16x16x16_bf16 v[2:5], v[20:21], v[6:7], v[2:5]
	s_nop 7
	v_cvt_pk_bf16_f32 v2, v2, v3
	v_cvt_pk_bf16_f32 v3, v4, v5
	ds_read_b64 v[4:5], v97 offset:1280
	s_waitcnt lgkmcnt(0)
	v_mfma_f32_16x16x16_bf16 v[2:5], v[4:5], v[2:3], 0
	s_nop 7
	v_cvt_pk_bf16_f32 v116, v2, v3
	v_cvt_pk_bf16_f32 v117, v4, v5
	ds_write_b64 v76, v[116:117] offset:64
	ds_read2_b64 v[18:21], v18 offset0:64 offset1:68
	ds_read_b64 v[4:5], v75 offset:96
	s_waitcnt lgkmcnt(0)
	v_lshlrev_b32_e32 v2, 16, v4
	v_and_b32_e32 v3, 0xffff0000, v4
	v_lshlrev_b32_e32 v4, 16, v5
	v_and_b32_e32 v5, 0xffff0000, v5
	s_nop 1
	v_mfma_f32_16x16x16_bf16 v[0:3], v[18:19], v[0:1], v[2:5]
	s_nop 2
	ds_read_b64 v[4:5], v98 offset:4672
	v_mfma_f32_16x16x16_bf16 v[0:3], v[20:21], v[6:7], v[0:3]
	s_waitcnt lgkmcnt(0)
	v_mfma_f32_16x16x16_bf16 v[0:3], v[4:5], v[116:117], v[0:3]
	s_nop 7
	v_cvt_pk_bf16_f32 v0, v0, v1
	v_cvt_pk_bf16_f32 v1, v2, v3
	ds_read_b64 v[2:3], v97 offset:1920
	s_waitcnt lgkmcnt(0)
	v_mfma_f32_16x16x16_bf16 v[0:3], v[2:3], v[0:1], 0
	s_nop 7
	v_cvt_pk_bf16_f32 v0, v0, v1
	v_cvt_pk_bf16_f32 v1, v2, v3
	ds_write_b64 v76, v[0:1] offset:96
	s_waitcnt lgkmcnt(0)
	s_barrier
; __device__ __forceinline__ unsigned pk2(float lo, float hi) { f32x2_t v = {lo, hi}; bf16x2_t b = __builtin_convertvector(v, bf16x2_t); return __builtin_bit_cast(unsigned, b); }
; __device__ __forceinline__ void chunk_item(const PAArgs& A, unsigned char* lds, int item, int tid, int wave, int lane, const ChunkRaw& RAW) {
;     ...
;     {
;         f32x4 c0, c1;
;         const int fl = lane * 4;
;         { const u32x2 w0 = *(const u32x2*)(RT + (tj0 * 16 + fr) * MST + ti * 16 + fq * 4), w1 = *(const u32x2*)(RT + (tj0 * 16 + 16 + fr) * MST + ti * 16 + fq * 4);
;           c0 = (f32x4){__uint_as_float(w0.x << 16), __uint_as_float(w0.x & 0xffff0000u), __uint_as_float(w0.y << 16), __uint_as_float(w0.y & 0xffff0000u)};
;           c1 = (f32x4){__uint_as_float(w1.x << 16), __uint_as_float(w1.x & 0xffff0000u), __uint_as_float(w1.y << 16), __uint_as_float(w1.y & 0xffff0000u)}; }
;         mm2(X1T, ARB, ti, tj0, fr, fq, c0, c1);
;         const int fpos = (((ti >> 1) * 64) + ((ti & 1) * 2 + (fq >> 1)) * 16 + fr) * 8 + (fq & 1) * 4;
;         *(u32x2*)(RPg + tj0 * 1024 + fpos) = (u32x2){pk2(c0[0], c0[1]), pk2(c0[2], c0[3])};
;         *(u32x2*)(RPg + (tj0 + 1) * 1024 + fpos) = (u32x2){pk2(c1[0], c1[1]), pk2(c1[2], c1[3])};
;         c0 = z4; c1 = z4; mm2(ZT, ARB, ti, tj0, fr, fq, c0, c1); mm2(VT, ARK, ti, tj0, fr, fq, c0, c1);
;         *(u32x2*)(Y0g + (ti * 4 + tj0) * 256 + fl) = (u32x2){pk2(c0[0], c0[1]), pk2(c0[2], c0[3])};
;         *(u32x2*)(Y0g + (ti * 4 + tj0 + 1) * 256 + fl) = (u32x2){pk2(c1[0], c1[1]), pk2(c1[2], c1[3])};
;         c0 = z4; c1 = z4; mm2(X1T, BHT, ti, tj0, fr, fq, c0, c1);
;         { const int chp = ti * 16 + fq * 4, cha = tj0 * 16 + fr, chb = cha + 16; const float wa = WCs[cha], wb = WCs[chb];
; #pragma unroll
;           for (int r = 0; r < 4; ++r) { c0[r] += (chp + r == cha) ? wa : 0.f; c1[r] += (chp + r == chb) ? wb : 0.f; }
;           *(u32x2*)(Pg + tj0 * 1024 + fpos) = (u32x2){pk2(c0[0], c0[1]), pk2(c0[2], c0[3])};
;           *(u32x2*)(Pg + (tj0 + 1) * 1024 + fpos) = (u32x2){pk2(c1[0], c1[1]), pk2(c1[2], c1[3])}; }
;         c0 = z4; c1 = z4; mm2(BHT, ZT, ti, tj0, fr, fq, c0, c1); mm2(KHT, VT, ti, tj0, fr, fq, c0, c1);
;         *(f32x4*)(Qg + (ti * 4 + tj0) * 256 + fl) = c0;
;         *(f32x4*)(Qg + (ti * 4 + tj0 + 1) * 256 + fl) = c1;
;     }
	ds_read_b64 v[2:3], v79 offset:27648
	ds_read_b64 v[4:5], v79 offset:29952
	s_waitcnt lgkmcnt(1)
	v_lshlrev_b32_e32 v0, 16, v2
	s_waitcnt lgkmcnt(0)
	v_lshlrev_b32_e32 v18, 16, v4
	v_and_b32_e32 v19, 0xffff0000, v4
	v_lshlrev_b32_e32 v20, 16, v5
	v_and_b32_e32 v21, 0xffff0000, v5
	ds_read_b128 v[4:7], v80
	ds_read_b128 v[116:119], v88
	ds_read_b128 v[120:123], v89
	v_and_b32_e32 v1, 0xffff0000, v2
	v_lshlrev_b32_e32 v2, 16, v3
	v_and_b32_e32 v3, 0xffff0000, v3
	s_waitcnt lgkmcnt(0)
	v_mfma_f32_16x16x32_bf16 v[18:21], v[4:7], v[120:123], v[18:21]
	v_mfma_f32_16x16x32_bf16 v[124:127], v[4:7], v[116:119], v[0:3]
	s_nop 2
	ds_read_b128 v[0:3], v80 offset:64
	ds_read_b128 v[128:131], v88 offset:64
	ds_read_b128 v[132:135], v89 offset:64
	s_waitcnt lgkmcnt(1)
	v_mfma_f32_16x16x32_bf16 v[124:127], v[0:3], v[128:131], v[124:127]
	s_waitcnt lgkmcnt(0)
	v_mfma_f32_16x16x32_bf16 v[18:21], v[0:3], v[132:135], v[18:21]
	s_nop 5
	v_cvt_pk_bf16_f32 v124, v124, v125
	v_cvt_pk_bf16_f32 v125, v126, v127
	v_lshl_add_u64 v[126:127], v[16:17], 0, s[50:51]
	v_add_co_u32_e32 v126, vcc, s6, v126
	s_brev_b32 s6, 32
	s_nop 0
	v_addc_co_u32_e32 v127, vcc, 0, v127, vcc
	v_cvt_pk_bf16_f32 v18, v18, v19
	v_cvt_pk_bf16_f32 v19, v20, v21
	global_store_dwordx2 v[126:127], v[18:19], off offset:2048
	ds_read_b128 v[18:21], v90
	s_waitcnt lgkmcnt(0)
	v_mfma_f32_16x16x32_bf16 v[116:119], v[18:21], v[116:119], 0
	global_store_dwordx2 v[126:127], v[124:125], off
	v_lshl_add_u64 v[16:17], v[16:17], 0, s[52:53]
	v_mfma_f32_16x16x32_bf16 v[18:21], v[18:21], v[120:123], 0
	ds_read_b128 v[120:123], v90 offset:64
	s_waitcnt lgkmcnt(0)
	v_mfma_f32_16x16x32_bf16 v[116:119], v[120:123], v[128:131], v[116:119]
	v_mfma_f32_16x16x32_bf16 v[18:21], v[120:123], v[132:135], v[18:21]
	ds_read_b128 v[120:123], v52 offset:55296
	ds_read_b128 v[124:127], v91
	ds_read_b128 v[128:131], v92
	s_waitcnt lgkmcnt(1)
	v_mfma_f32_16x16x32_bf16 v[116:119], v[120:123], v[124:127], v[116:119]
	s_waitcnt lgkmcnt(0)
	v_mfma_f32_16x16x32_bf16 v[18:21], v[120:123], v[128:131], v[18:21]
	ds_read_b128 v[120:123], v52 offset:55360
	ds_read_b128 v[124:127], v91 offset:64
	ds_read_b128 v[128:131], v92 offset:64
	s_waitcnt lgkmcnt(1)
	v_mfma_f32_16x16x32_bf16 v[116:119], v[120:123], v[124:127], v[116:119]
	v_perm_b32 v126, v106, v104, s37
	v_perm_b32 v127, v105, v103, s37
	s_waitcnt lgkmcnt(0)
	v_mfma_f32_16x16x32_bf16 v[18:21], v[120:123], v[128:131], v[18:21]
	s_nop 3
	v_cvt_pk_bf16_f32 v116, v116, v117
	v_cvt_pk_bf16_f32 v117, v118, v119
	v_lshl_add_u64 v[118:119], v[14:15], 0, s[50:51]
	v_add_co_u32_e32 v118, vcc, s6, v118
	s_mov_b32 s6, 0x1b800000
	s_nop 0
	v_addc_co_u32_e32 v119, vcc, 0, v119, vcc
	v_cvt_pk_bf16_f32 v18, v18, v19
	v_cvt_pk_bf16_f32 v19, v20, v21
	global_store_dwordx2 v[118:119], v[116:117], off
	global_store_dwordx2 v[118:119], v[18:19], off offset:512
	ds_read_b128 v[18:21], v53 offset:36864
	ds_read_b128 v[116:119], v53 offset:39168
	s_waitcnt lgkmcnt(1)
	v_mfma_f32_16x16x32_bf16 v[18:21], v[4:7], v[18:21], 0
	v_lshl_add_u64 v[14:15], v[14:15], 0, s[52:53]
	s_waitcnt lgkmcnt(0)
	v_mfma_f32_16x16x32_bf16 v[4:7], v[4:7], v[116:119], 0
	ds_read_b128 v[116:119], v53 offset:36928
	ds_read_b128 v[120:123], v53 offset:39232
	s_waitcnt lgkmcnt(1)
	v_mfma_f32_16x16x32_bf16 v[18:21], v[0:3], v[116:119], v[18:21]
	s_waitcnt lgkmcnt(0)
	v_mfma_f32_16x16x32_bf16 v[0:3], v[0:3], v[120:123], v[4:7]
	s_nop 2
	ds_read_b32 v6, v81
	ds_read_b32 v115, v82
	s_waitcnt lgkmcnt(1)
	v_cndmask_b32_e64 v4, 0, v6, s[84:85]
	v_add_f32_e32 v18, v18, v4
	v_cndmask_b32_e64 v4, 0, v6, s[86:87]
	v_add_f32_e32 v19, v19, v4
	s_waitcnt lgkmcnt(0)
	v_cndmask_b32_e64 v5, 0, v115, s[90:91]
	v_cndmask_b32_e64 v4, 0, v115, s[88:89]
	v_pk_add_f32 v[0:1], v[0:1], v[4:5]
	v_cndmask_b32_e64 v5, 0, v6, s[92:93]
	v_cndmask_b32_e64 v4, 0, v6, s[94:95]
	v_pk_add_f32 v[4:5], v[20:21], v[4:5]
	v_cndmask_b32_e64 v7, 0, v115, s[96:97]
	v_cndmask_b32_e64 v6, 0, v115, s[18:19]
	v_pk_add_f32 v[2:3], v[2:3], v[6:7]
	v_cvt_pk_bf16_f32 v7, v4, v5
	v_lshl_add_u64 v[4:5], v[12:13], 0, s[50:51]
	v_add_co_u32_e32 v4, vcc, s6, v4
	v_cvt_pk_bf16_f32 v6, v18, v19
	s_nop 0
	v_addc_co_u32_e32 v5, vcc, 0, v5, vcc
	v_cvt_pk_bf16_f32 v0, v0, v1
	v_cvt_pk_bf16_f32 v1, v2, v3
	global_store_dwordx2 v[4:5], v[6:7], off
	global_store_dwordx2 v[4:5], v[0:1], off offset:2048
	ds_read_b128 v[0:3], v52 offset:36864
	ds_read_b128 v[4:7], v93
	ds_read_b128 v[18:21], v94
	s_waitcnt lgkmcnt(1)
	v_mfma_f32_16x16x32_bf16 v[4:7], v[0:3], v[4:7], 0
	v_lshl_add_u64 v[12:13], v[12:13], 0, s[52:53]
	s_and_b64 vcc, exec, s[40:41]
	s_waitcnt lgkmcnt(0)
	v_mfma_f32_16x16x32_bf16 v[0:3], v[0:3], v[18:21], 0
	ds_read_b128 v[18:21], v52 offset:36928
	ds_read_b128 v[116:119], v93 offset:64
	ds_read_b128 v[120:123], v94 offset:64
	s_waitcnt lgkmcnt(1)
	v_mfma_f32_16x16x32_bf16 v[4:7], v[18:21], v[116:119], v[4:7]
	s_waitcnt lgkmcnt(0)
	v_mfma_f32_16x16x32_bf16 v[0:3], v[18:21], v[120:123], v[0:3]
	ds_read_b128 v[18:21], v52 offset:46080
	ds_read_b128 v[116:119], v53 offset:55296
	ds_read_b128 v[120:123], v53 offset:57600
	s_waitcnt lgkmcnt(1)
	v_mfma_f32_16x16x32_bf16 v[4:7], v[18:21], v[116:119], v[4:7]
	s_waitcnt lgkmcnt(0)
	v_mfma_f32_16x16x32_bf16 v[0:3], v[18:21], v[120:123], v[0:3]
	ds_read_b128 v[18:21], v52 offset:46144
	ds_read_b128 v[116:119], v53 offset:55360
	ds_read_b128 v[120:123], v53 offset:57664
	s_waitcnt lgkmcnt(1)
	v_mfma_f32_16x16x32_bf16 v[4:7], v[18:21], v[116:119], v[4:7]
	s_waitcnt lgkmcnt(0)
	v_mfma_f32_16x16x32_bf16 v[0:3], v[18:21], v[120:123], v[0:3]
	s_nop 5
	global_store_dwordx4 v[10:11], v[4:7], off offset:-1024
	s_nop 0
	global_store_dwordx4 v[10:11], v[0:3], off
	s_nop 1
	v_perm_b32 v3, v114, v112, s37
	v_perm_b32 v5, v113, v111, s37
	v_perm_b32 v122, v110, v108, s37
	v_perm_b32 v123, v109, v107, s37
	v_perm_b32 v6, v102, v100, s37
	v_perm_b32 v7, v101, v99, s37
	v_lshl_add_u64 v[10:11], v[10:11], 0, s[24:25]
	s_cbranch_vccnz .LBB0_437

; __device__ __forceinline__ unsigned xb_add(unsigned* p, unsigned v) { return __hip_atomic_fetch_add(p, v, __ATOMIC_RELAXED, __HIP_MEMORY_SCOPE_AGENT); }
; __device__ __forceinline__ void xcd_barrier(const XcdBarrier& b) {
;     asm volatile("s_waitcnt vmcnt(0)" ::: "memory");
;     __syncthreads();
;     if (threadIdx.x == 0) {
;         unsigned* bar = b.bar;
;         __builtin_amdgcn_s_waitcnt(0);
;         unsigned nloc = b.st[0], nx = b.st[1];
;         if (nloc == 0u) { xcd_barrier_complete(bar, b.x, nloc, nx); b.st[0] = nloc; b.st[1] = nx; }
;         const unsigned old = xb_add(&bar[XB_XSUB(b.x)], 1u);
.LBB0_437:
	s_setprio 0
	s_waitcnt vmcnt(0)
	v_readlane_b32 s36, v240, 4
	v_readlane_b32 s78, v240, 1
	s_barrier
	s_mov_b64 s[0:1], exec
	v_readlane_b32 s66, v241, 53
	v_readlane_b32 s67, v241, 54
	v_readlane_b32 s68, v241, 51
	v_readlane_b32 s92, v241, 55
	v_readlane_b32 s76, v241, 57
	v_readlane_b32 s96, v242, 35
	v_readlane_b32 s94, v242, 37
	v_readlane_b32 s64, v242, 39
	v_readlane_b32 s88, v242, 41
	v_readlane_b32 s60, v241, 21
	v_readlane_b32 s72, v241, 28
	v_readlane_b32 s62, v241, 30
	s_and_b64 s[2:3], s[0:1], s[66:67]
	v_readlane_b32 s69, v241, 52
	v_readlane_b32 s93, v241, 56
	v_readlane_b32 s77, v241, 58
	v_readlane_b32 s90, v242, 34
	v_readlane_b32 s97, v242, 36
	v_readlane_b32 s95, v242, 38
	v_readlane_b32 s65, v242, 40
	v_readlane_b32 s89, v242, 42
	v_readlane_b32 s61, v241, 22
	v_readlane_b32 s73, v241, 29
	v_readlane_b32 s63, v241, 31
	v_readlane_b32 s79, v240, 2
	s_mov_b64 exec, s[2:3]
	s_cbranch_execz .LBB0_489
	s_add_i32 s2, 0, 0x23ff0
	v_mov_b32_e32 v0, s2
	s_waitcnt vmcnt(0) expcnt(0) lgkmcnt(0)
	ds_read_b32 v2, v0
	s_add_i32 s2, 0, 0x23ff4
	v_mov_b32_e32 v0, s2
	ds_read_b32 v0, v0
	s_waitcnt lgkmcnt(1)
	v_cmp_ne_u32_e32 vcc, 0, v2
	s_cbranch_vccnz .LBB0_453
	s_mov_b32 s2, 1
	v_mov_b32_e32 v16, 0
	s_branch .LBB0_441

; __device__ __forceinline__ void chunk_out(const PBArgs& A, unsigned char* lds, int G_, int wave, int lane) {
;     const bf16* Y0g = (const bf16*)(A.dout + DO_Y0); const bf16* RPg = (const bf16*)(A.dout + DO_RP); const bf16* MC = (const bf16*)(A.ws + WS_MC);
;     const bf16* Vr = (const bf16*)(A.ws + WS_V); const bf16* Gt = (const bf16*)(A.ws + WS_HBUF); const float* RK = (const float*)(A.ws + WS_RK);
;     bf16* YA = (bf16*)(A.ws + WS_YA);
;     const int fr = lane & 15, fq = lane >> 4, tt = wave & 3, half = wave >> 2;
;     unsigned char* ostg = lds + wave * 2304;
;     bf16x8 nbR[2], naM[4][2]; u32x2 ny0[4]; u32x4 nrv[2], nrg[2]; f32x4 nr4;
;     ...
;     const int it0 = blockIdx.x * 2 + half;
;     if (it0 < 4096) CO_LOAD(it0);
;     ...
;             const f32x4 lg = *(const f32x4*)(A.lnx_g + h * 64 + vi * 16 + fq * 4), lb = *(const f32x4*)(A.lnx_b + h * 64 + vi * 16 + fq * 4);
.LBB0_575:
	s_or_b64 exec, exec, s[0:1]
	s_lshl_b32 s0, s68, 1
	v_readlane_b32 s1, v241, 27
	s_add_i32 s0, s1, s0
	s_cmpk_lt_i32 s0, 0x1000
	s_movk_i32 s2, 0x1000
	s_waitcnt lgkmcnt(0)
	s_barrier
	s_waitcnt vmcnt(3)
	v_mbcnt_lo_u32_b32 v60, -1, 0
	v_mbcnt_hi_u32_b32 v60, -1, v60
	s_cbranch_scc0 .LBB0_578
	s_add_u32 s3, s28, 0x19800000
	s_addc_u32 s16, s29, 0
	s_add_u32 s14, s26, 0x4000000
	s_addc_u32 s15, s27, 0
	v_readlane_b32 s1, v242, 17
	s_add_u32 s8, s26, 0x6000000
	s_mulk_i32 s1, 0x900
	s_addc_u32 s9, s27, 0
	s_add_i32 s17, s1, 0
	v_readlane_b32 s1, v242, 0
	s_bfe_u32 s18, s1, 0x20006
	s_ashr_i32 s1, s0, 31
	v_lshlrev_b32_e32 v94, 3, v60
	s_lshl_b64 s[6:7], s[0:1], 13
	v_lshl_add_u32 v0, s18, 10, v94
	s_add_u32 s10, s8, s6
	v_ashrrev_i32_e32 v1, 31, v0
	s_addc_u32 s11, s9, s7
	v_lshlrev_b64 v[62:63], 1, v[0:1]
	v_lshl_add_u64 v[4:5], s[10:11], 0, v[62:63]
	s_add_u32 s10, s3, s6
	s_addc_u32 s11, s16, s7
	v_lshlrev_b32_e32 v8, 2, v60
	s_add_u32 s6, s14, s6
	v_ashrrev_i32_e32 v9, 31, v8
	s_addc_u32 s7, s15, s7
	v_lshlrev_b64 v[64:65], 1, v[8:9]
	s_mov_b32 s5, 0
	v_lshl_add_u64 v[8:9], s[6:7], 0, v[64:65]
	s_lshl_b32 s4, s18, 9
	v_ashrrev_i32_e32 v95, 31, v94
	v_lshl_add_u64 v[20:21], v[8:9], 0, s[4:5]
	v_add_u32_e32 v96, 0x800, v94
	v_add_u32_e32 v98, 0xa00, v94
	v_add_u32_e32 v100, 0xc00, v94
	v_add_u32_e32 v102, 0xe00, v94
	v_lshl_add_u64 v[10:11], v[94:95], 1, s[10:11]
	v_ashrrev_i32_e32 v97, 31, v96
	v_ashrrev_i32_e32 v99, 31, v98
	v_add_co_u32_e32 v40, vcc, s2, v20
	v_ashrrev_i32_e32 v101, 31, v100
	v_ashrrev_i32_e32 v103, 31, v102
	global_load_dwordx4 v[0:3], v[4:5], off
	s_nop 0
	global_load_dwordx4 v[4:7], v[4:5], off offset:1024
	s_nop 0
	global_load_dwordx4 v[32:35], v[10:11], off
	global_load_dwordx4 v[36:39], v[10:11], off offset:1024
	global_load_dwordx4 v[16:19], v[10:11], off offset:2048
	global_load_dwordx4 v[24:27], v[10:11], off offset:3072
	global_load_dwordx2 v[112:113], v[20:21], off
	global_load_dwordx2 v[108:109], v[20:21], off offset:2048
	v_lshl_add_u64 v[8:9], v[96:97], 1, s[10:11]
	v_lshl_add_u64 v[12:13], v[98:99], 1, s[10:11]
	v_addc_co_u32_e32 v41, vcc, 0, v21, vcc
	v_lshl_add_u64 v[20:21], v[100:101], 1, s[10:11]
	v_lshl_add_u64 v[28:29], v[102:103], 1, s[10:11]
	s_ashr_i32 s10, s0, 6
	s_ashr_i32 s11, s10, 31
	s_lshl_b32 s1, s0, 6
	s_lshl_b64 s[12:13], s[10:11], 12
	s_and_b32 s1, s1, 0xfc0
	s_or_b32 s7, s12, s1
	s_lshl_b32 s6, s18, 4
	s_or_b32 s12, s7, s6
	s_lshl_b64 s[12:13], s[12:13], 7
	global_load_dwordx4 v[8:11], v[8:9], off
	s_nop 0
	global_load_dwordx4 v[12:15], v[12:13], off
	s_nop 0
	global_load_dwordx4 v[20:23], v[20:21], off
	s_nop 0
	global_load_dwordx4 v[28:31], v[28:29], off
	s_nop 0
	global_load_dwordx2 v[114:115], v[40:41], off
	global_load_dwordx2 v[110:111], v[40:41], off offset:2048
	s_add_u32 s18, s70, s12
	v_lshlrev_b32_e32 v40, 4, v60
	s_addc_u32 s19, s71, s13
	v_and_b32_e32 v66, 0x70, v40
	v_mov_b32_e32 v67, 0
	v_lshl_add_u64 v[48:49], s[18:19], 0, v[66:67]
	v_readlane_b32 s18, v241, 19
	v_readlane_b32 s19, v241, 20
	s_add_u32 s12, s18, s12
	s_addc_u32 s13, s19, s13
	v_lshl_add_u64 v[50:51], s[12:13], 0, v[66:67]
	s_ashr_i32 s12, s0, 9
	s_ashr_i32 s13, s12, 31
	v_and_b32_e32 v92, 15, v60
	s_lshl_b64 s[12:13], s[12:13], 12
	s_waitcnt vmcnt(16)
	v_or_b32_e32 v56, s12, v92
	v_ashrrev_i32_e32 v104, 3, v60
	v_or_b32_e32 v56, s1, v56
	v_add_u32_e32 v106, 8, v104
	v_or_b32_e32 v56, s6, v56
	v_mov_b32_e32 v57, s13
	v_readlane_b32 s22, v241, 48
	v_ashrrev_i32_e32 v105, 31, v104
	v_ashrrev_i32_e32 v107, 31, v106
	v_lshlrev_b64 v[56:57], 7, v[56:57]
	v_readlane_b32 s23, v241, 49
	s_lshl_b32 s1, s10, 4
	v_lshlrev_b64 v[40:41], 7, v[104:105]
	v_lshlrev_b64 v[52:53], 7, v[106:107]
	v_lshl_add_u64 v[56:57], s[22:23], 0, v[56:57]
	s_and_b32 s10, s1, 0x70
	s_mov_b32 s11, s5
	v_lshl_add_u64 v[42:43], v[48:49], 0, v[40:41]
	v_lshl_add_u64 v[40:41], v[50:51], 0, v[40:41]
	v_lshl_add_u64 v[48:49], v[48:49], 0, v[52:53]
	v_lshl_add_u64 v[50:51], v[50:51], 0, v[52:53]
	v_lshl_add_u64 v[56:57], v[56:57], 0, s[10:11]
	global_load_dwordx4 v[44:47], v[42:43], off
	s_nop 0
	global_load_dwordx4 v[40:43], v[40:41], off
	s_nop 0
	global_load_dwordx4 v[52:55], v[48:49], off
	s_nop 0
	global_load_dwordx4 v[48:51], v[50:51], off
	v_ashrrev_i32_e32 v70, 4, v60
	global_load_dwordx4 v[56:59], v[56:57], off
	s_movk_i32 s1, 0x90
	v_mov_b32_e32 v71, s17
	v_lshlrev_b32_e32 v74, 3, v70
	v_lshlrev_b32_e32 v70, 2, v70
	v_readlane_b32 s36, v242, 1
	v_mad_u32_u24 v73, v92, s1, v71
	v_lshl_add_u64 v[64:65], s[14:15], 0, v[64:65]
	v_ashrrev_i32_e32 v71, 31, v70
	v_readlane_b32 s38, v242, 3
	v_readlane_b32 s39, v242, 4
	v_readlane_b32 s40, v242, 5
	v_readlane_b32 s41, v242, 6
	v_lshlrev_b64 v[60:61], 6, v[104:105]
	v_lshlrev_b64 v[68:69], 6, v[106:107]
	v_add_u32_e32 v72, s17, v66
	v_lshl_add_u64 v[116:117], s[70:71], 0, v[66:67]
	v_lshl_add_u64 v[118:119], s[18:19], 0, v[66:67]
	v_lshl_add_u64 v[120:121], s[74:75], 0, v[66:67]
	v_mul_lo_u32 v66, v104, s1
	v_lshl_add_u64 v[122:123], v[64:65], 0, s[4:5]
	v_lshl_add_u64 v[124:125], s[8:9], 0, v[62:63]
	v_lshlrev_b64 v[62:63], 2, v[70:71]
	s_mov_b64 s[18:19], s[38:39]
	s_mov_b64 s[20:21], s[40:41]
	s_lshl_b32 s1, s68, 7
	v_readlane_b32 s4, v241, 23
	s_mov_b32 s7, s5
	s_lshl_b32 s10, s30, 1
	v_lshl_add_u64 v[126:127], s[18:19], 0, v[62:63]
	v_lshl_add_u64 v[128:129], s[20:21], 0, v[62:63]
	s_add_i32 s11, s1, s4
	s_lshl_b32 s12, s30, 7
	v_add_u32_e32 v93, v72, v66
	v_add_u32_e32 v144, v73, v74
	v_lshlrev_b64 v[130:131], 1, v[60:61]
	v_lshlrev_b64 v[132:133], 1, v[68:69]
	v_mov_b32_e32 v145, 0x3a27c5ac
	v_readlane_b32 s37, v242, 2
	v_readlane_b32 s42, v242, 7
	v_readlane_b32 s43, v242, 8
	v_readlane_b32 s44, v242, 9
	v_readlane_b32 s45, v242, 10
	v_readlane_b32 s46, v242, 11
	v_readlane_b32 s47, v242, 12
	v_readlane_b32 s48, v242, 13
	v_readlane_b32 s49, v242, 14
	v_readlane_b32 s50, v242, 15
	v_readlane_b32 s51, v242, 16
	v_mbcnt_lo_u32_b32 v154, -1, 0
	v_mbcnt_hi_u32_b32 v154, -1, v154
	v_readlane_b32 s98, v242, 17
	s_lshl_b32 s99, s98, 8
	v_lshl_add_u32 v155, v154, 2, s99
	v_readlane_b32 s100, v242, 3
	v_readlane_b32 s101, v242, 4
	s_nop 4
	global_load_dword v156, v155, s[100:101]
	v_readlane_b32 s100, v242, 5
	v_readlane_b32 s101, v242, 6
	s_nop 4
	global_load_dword v157, v155, s[100:101]
	v_add_u32_e32 v158, 32768, v155
	s_and_b32 s100, s98, 3
	s_lshl_b32 s101, s100, 9
	v_add_u32_e32 v170, s101, v94
	v_mov_b32_e32 v171, 0
	v_add_u32_e32 v172, 0x800, v170
	v_mov_b32_e32 v173, 0
	s_lshl_b32 s101, s100, 10
	s_lshr_b32 s100, s98, 2
	s_lshl_b32 s100, s100, 13
	v_lshlrev_b32_e32 v168, 4, v154
	v_add_u32_e32 v168, s100, v168
	v_add_u32_e32 v168, 40960, v168
	v_add_u32_e32 v166, s101, v168
	s_mov_b32 s99, 0
	s_mov_b32 s100, s0
	s_ashr_i32 s101, s0, 31
	s_lshl_b64 s[100:101], s[100:101], 13
	s_add_u32 s100, s100, s3
	s_addc_u32 s101, s101, s16
	v_lshl_add_u64 v[164:165], v[170:171], 1, s[100:101]
	v_lshl_add_u64 v[178:179], v[172:173], 1, s[100:101]
	global_load_dwordx4 v[160:163], v[164:165], off
	global_load_dwordx4 v[174:177], v[178:179], off
	s_waitcnt vmcnt(0)
; #define LDS_WAIT() asm volatile("s_waitcnt lgkmcnt(0)" ::: "memory")
; __device__ __forceinline__ void chunk_out(const PBArgs& A, unsigned char* lds, int G_, int wave, int lane) {
;     ...
;     for (int it = it0; it < 4096; it += 2 * G_) {
;         const int bh = it >> 6, ck = it & 63, b = bh >> 3, h = bh & 7;
;         bf16x8 bR[2], aM[4][2]; u32x2 y0[4], vv[4], gg[4]; u32x4 rv[2], rg[2];
; #pragma unroll
;         for (int ks = 0; ks < 2; ++ks) bR[ks] = nbR[ks];
; #pragma unroll
;         for (int vi = 0; vi < 4; ++vi) { aM[vi][0] = naM[vi][0]; aM[vi][1] = naM[vi][1]; y0[vi] = ny0[vi]; }
; #pragma unroll
;         for (int j = 0; j < 2; ++j) { rv[j] = nrv[j]; rg[j] = nrg[j]; }
;         const float rk = (nr4[0] + nr4[1]) + (nr4[2] + nr4[3]);
;         {
; #pragma unroll
;             for (int j = 0; j < 2; ++j) { const int tk = (lane >> 3) + 8 * j, c16 = lane & 7; *(u32x4*)(ostg + tk * 144 + c16 * 16) = rv[j]; }
;             LDS_WAIT();
; #pragma unroll
;             for (int vi = 0; vi < 4; ++vi) vv[vi] = *(const u32x2*)(ostg + fr * 144 + (vi * 16 + fq * 4) * 2);
;             LDS_WAIT();
; #pragma unroll
;             for (int j = 0; j < 2; ++j) { const int tk = (lane >> 3) + 8 * j, c16 = lane & 7; *(u32x4*)(ostg + tk * 144 + c16 * 16) = rg[j]; }
;             LDS_WAIT();
; #pragma unroll
;             for (int vi = 0; vi < 4; ++vi) gg[vi] = *(const u32x2*)(ostg + fr * 144 + (vi * 16 + fq * 4) * 2);
;             LDS_WAIT();
;         }
;         f32x4 c[4];
; #pragma unroll
;         for (int vi = 0; vi < 4; ++vi) {
;             c[vi] = bf4(y0[vi]);
; #pragma unroll
;             for (int ks = 0; ks < 2; ++ks) c[vi] = __builtin_amdgcn_mfma_f32_16x16x32_bf16(aM[vi][ks], bR[ks], c[vi], 0, 0, 0);
;         }
;         { const int itn = (it + 2 * G_ < 4096) ? it + 2 * G_ : it; CO_LOAD(itn); }
;         float sm = 0.f;
; #pragma unroll
;         for (int vi = 0; vi < 4; ++vi) sm += (c[vi][0] + c[vi][1]) + (c[vi][2] + c[vi][3]);
;         sm = rows4_sum(sm);
;         const float mu = sm * (1.0f / 64.0f);
;         float q = 0.f;
; #pragma unroll
;         for (int vi = 0; vi < 4; ++vi) { c[vi] = c[vi] - mu; q += (c[vi][0] * c[vi][0] + c[vi][1] * c[vi][1]) + (c[vi][2] * c[vi][2] + c[vi][3] * c[vi][3]); }
;         q = rows4_sum(q);
;         const float rs = rsqrtf(q * (1.0f / 64.0f) + 64e-5f);
	ds_write_b32 v158, v156
	ds_write_b32 v158, v157 offset:2048
	v_lshrrev_b32_e32 v159, 4, v154
	v_lshlrev_b32_e32 v159, 4, v159
	v_add_u32_e32 v159, 32768, v159
	s_waitcnt lgkmcnt(0)
	s_barrier
	s_cmp_lt_u32 s98, 4
	s_cbranch_scc1 .Lp4c_noprio
	s_setprio 1
.Lp4c_noprio:
.LBB0_577:
	s_waitcnt vmcnt(4)
	v_add_u32_e32 v167, s99, v166
	ds_write_b128 v167, v[160:163]
	ds_write_b128 v167, v[174:177] offset:4096
	ds_write_b128 v93, v[44:47]
	s_waitcnt vmcnt(2)
	ds_write_b128 v93, v[52:55] offset:1152
	s_waitcnt lgkmcnt(0)
	s_barrier
	v_add_u32_e32 v169, s99, v168
	ds_read_b128 v[32:35], v169
	ds_read_b128 v[36:39], v169 offset:1024
	ds_read_b128 v[16:19], v169 offset:2048
	ds_read_b128 v[24:27], v169 offset:3072
	ds_read_b128 v[8:11], v169 offset:4096
	ds_read_b128 v[12:15], v169 offset:5120
	ds_read_b128 v[20:23], v169 offset:6144
	ds_read_b128 v[28:31], v169 offset:7168
	s_xor_b32 s99, s99, 0x4000
	ds_read2_b64 v[68:71], v144 offset1:4
	ds_read2_b64 v[60:63], v144 offset0:8 offset1:12
	s_waitcnt lgkmcnt(0)
	ds_write_b128 v93, v[40:43]
	s_waitcnt vmcnt(1)
	ds_write_b128 v93, v[48:51] offset:1152
	v_lshlrev_b32_e32 v40, 16, v112
	v_and_b32_e32 v41, 0xffff0000, v112
	v_lshlrev_b32_e32 v42, 16, v113
	v_and_b32_e32 v43, 0xffff0000, v113
	s_ashr_i32 s8, s0, 9
	s_and_b32 s14, s0, 0x1c0
	v_mfma_f32_16x16x32_bf16 v[32:35], v[32:35], v[0:3], v[40:43]
	s_add_i32 s13, s0, s10
	s_cmpk_lt_i32 s13, 0x1000
	s_cselect_b64 s[18:19], -1, 0
	v_mfma_f32_16x16x32_bf16 v[88:91], v[36:39], v[4:7], v[32:35]
	s_and_b64 vcc, s[18:19], exec
	s_cselect_b32 s18, s13, s0
	s_ashr_i32 s19, s18, 31
	s_nop 0
	v_lshlrev_b32_e32 v32, 16, v108
	v_and_b32_e32 v33, 0xffff0000, v108
	v_lshlrev_b32_e32 v34, 16, v109
	v_and_b32_e32 v35, 0xffff0000, v109
	v_add_f32_e32 v136, v88, v89
	v_add_f32_e32 v137, v90, v91
	v_mfma_f32_16x16x32_bf16 v[16:19], v[16:19], v[0:3], v[32:35]
	v_add_f32_e32 v136, v136, v137
	v_add_f32_e32 v136, 0, v136
	s_lshl_b64 s[0:1], s[18:19], 13
	v_mfma_f32_16x16x32_bf16 v[76:79], v[24:27], v[4:7], v[16:19]
	s_add_u32 s20, s3, s0
	s_addc_u32 s21, s16, s1
	s_waitcnt lgkmcnt(0)
	ds_read2_b64 v[72:75], v144 offset1:4
	ds_read2_b64 v[64:67], v144 offset0:8 offset1:12
	v_lshlrev_b32_e32 v16, 16, v114
	v_and_b32_e32 v17, 0xffff0000, v114
	v_lshlrev_b32_e32 v18, 16, v115
	v_and_b32_e32 v19, 0xffff0000, v115
	v_add_f32_e32 v137, v76, v77
	v_add_f32_e32 v138, v78, v79
	v_mfma_f32_16x16x32_bf16 v[8:11], v[8:11], v[0:3], v[16:19]
	v_add_f32_e32 v137, v137, v138
	v_add_f32_e32 v136, v136, v137
	s_waitcnt lgkmcnt(0)
	v_mfma_f32_16x16x32_bf16 v[80:83], v[12:15], v[4:7], v[8:11]
	v_lshl_add_u64 v[12:13], v[98:99], 1, s[20:21]
	s_waitcnt vmcnt(0)
	v_mov_b32_e32 v44, v57
	v_mov_b32_e32 v45, v58
	s_nop 0
	v_lshlrev_b32_e32 v8, 16, v110
	v_and_b32_e32 v9, 0xffff0000, v110
	v_lshlrev_b32_e32 v10, 16, v111
	v_and_b32_e32 v11, 0xffff0000, v111
	v_add_f32_e32 v137, v80, v81
	v_add_f32_e32 v138, v82, v83
	v_mfma_f32_16x16x32_bf16 v[0:3], v[20:23], v[0:3], v[8:11]
	v_add_f32_e32 v137, v137, v138
	v_add_f32_e32 v136, v136, v137
	v_lshl_add_u64 v[20:21], v[122:123], 0, s[0:1]
	v_mfma_f32_16x16x32_bf16 v[84:87], v[28:31], v[4:7], v[0:3]
	v_lshl_add_u64 v[4:5], v[124:125], 0, s[0:1]
	v_add_co_u32_e64 v40, s[0:1], s2, v20
	v_lshl_add_u64 v[8:9], v[94:95], 1, s[20:21]
	v_lshl_add_u64 v[164:165], v[170:171], 1, s[20:21]
	v_lshl_add_u64 v[178:179], v[172:173], 1, s[20:21]
	s_nop 0
	v_addc_co_u32_e64 v41, s[0:1], 0, v21, s[0:1]
	s_nop 2
	v_add_f32_e32 v137, v84, v85
	v_add_f32_e32 v138, v86, v87
	v_add_f32_e32 v137, v137, v138
	v_add_f32_e32 v136, v136, v137
	v_mov_b32_e32 v137, v136
	s_nop 1
	v_permlane32_swap_b32_e32 v136, v137
	v_add_f32_e32 v136, v136, v137
	v_mov_b32_e32 v137, v136
	s_nop 1
	v_permlane16_swap_b32_e32 v136, v137
	v_add_f32_e32 v136, v136, v137
	v_fmamk_f32 v151, v136, 0xbc800000, v91
	v_fmac_f32_e32 v89, 0xbc800000, v136
	v_fmamk_f32 v150, v136, 0xbc800000, v90
	v_fmamk_f32 v88, v136, 0xbc800000, v88
	v_mul_f32_e32 v90, v89, v89
	v_mul_f32_e32 v91, v151, v151
	v_fmac_f32_e32 v90, v88, v88
	v_fmac_f32_e32 v91, v150, v150
	s_ashr_i32 s0, s18, 6
	v_add_f32_e32 v137, v90, v91
	v_fmamk_f32 v91, v136, 0xbc800000, v79
	v_fmac_f32_e32 v77, 0xbc800000, v136
	s_ashr_i32 s1, s0, 31
	v_fmamk_f32 v90, v136, 0xbc800000, v78
	v_fmamk_f32 v76, v136, 0xbc800000, v76
	v_mul_f32_e32 v78, v77, v77
	v_mul_f32_e32 v79, v91, v91
	global_load_dwordx4 v[0:3], v[4:5], off nt
	s_nop 0
	global_load_dwordx4 v[4:7], v[4:5], off offset:1024 nt
	s_nop 0
	global_load_dwordx4 v[160:163], v[164:165], off nt
	global_load_dwordx4 v[174:177], v[178:179], off nt
	global_load_dwordx2 v[112:113], v[20:21], off nt
	s_nop 0
	s_nop 0
	global_load_dwordx2 v[108:109], v[20:21], off offset:2048 nt
	v_lshl_add_u64 v[8:9], v[96:97], 1, s[20:21]
	v_lshl_add_u64 v[20:21], v[100:101], 1, s[20:21]
	v_lshl_add_u64 v[28:29], v[102:103], 1, s[20:21]
	s_lshl_b64 s[20:21], s[0:1], 12
	s_lshl_b32 s1, s18, 6
	s_ashr_i32 s18, s18, 9
	v_fmac_f32_e32 v78, v76, v76
	v_fmac_f32_e32 v79, v90, v90
	s_ashr_i32 s19, s18, 31
	v_add_f32_e32 v78, v78, v79
	v_fmamk_f32 v83, v136, 0xbc800000, v83
	v_fmac_f32_e32 v81, 0xbc800000, v136
	v_mov_b32_e32 v57, v59
	s_lshl_b64 s[18:19], s[18:19], 12
	v_add_f32_e32 v78, v137, v78
	v_fmamk_f32 v82, v136, 0xbc800000, v82
	v_fmamk_f32 v80, v136, 0xbc800000, v80
	v_mul_f32_e32 v79, v81, v81
	v_mul_f32_e32 v137, v83, v83
	v_pk_add_f32 v[134:135], v[44:45], v[56:57]
	s_and_b32 s1, s1, 0xfc0
	v_or_b32_e32 v56, s18, v92
	v_fmac_f32_e32 v79, v80, v80
	v_fmac_f32_e32 v137, v82, v82
	v_or_b32_e32 v56, s1, v56
	v_add_f32_e32 v79, v79, v137
	v_mov_b32_e32 v57, s19
	v_or_b32_e32 v56, s6, v56
	v_add_f32_e32 v137, v79, v78
; __device__ __forceinline__ unsigned pk2(float lo, float hi) { f32x2_t v = {lo, hi}; bf16x2_t b = __builtin_convertvector(v, bf16x2_t); return __builtin_bit_cast(unsigned, b); }
; #define LDS_WAIT() asm volatile("s_waitcnt lgkmcnt(0)" ::: "memory")
; __device__ __forceinline__ f32x4 bf4(u32x2 w) { return (f32x4){__uint_as_float(w.x << 16), __uint_as_float(w.x & 0xffff0000u), __uint_as_float(w.y << 16), __uint_as_float(w.y & 0xffff0000u)}; }
; __device__ __forceinline__ void chunk_out(const PBArgs& A, unsigned char* lds, int G_, int wave, int lane) {
;     ...
;         float sm = 0.f;
; #pragma unroll
;         for (int vi = 0; vi < 4; ++vi) sm += (c[vi][0] + c[vi][1]) + (c[vi][2] + c[vi][3]);
;         sm = rows4_sum(sm);
;         const float mu = sm * (1.0f / 64.0f);
;         float q = 0.f;
; #pragma unroll
;         for (int vi = 0; vi < 4; ++vi) { c[vi] = c[vi] - mu; q += (c[vi][0] * c[vi][0] + c[vi][1] * c[vi][1]) + (c[vi][2] * c[vi][2] + c[vi][3] * c[vi][3]); }
;         q = rows4_sum(q);
;         const float rs = rsqrtf(q * (1.0f / 64.0f) + 64e-5f);
; #pragma unroll
;         for (int vi = 0; vi < 4; ++vi) {
;             const f32x4 lg = *(const f32x4*)(A.lnx_g + h * 64 + vi * 16 + fq * 4), lb = *(const f32x4*)(A.lnx_b + h * 64 + vi * 16 + fq * 4);
;             const f32x4 o = (c[vi] * rs * lg + lb + bf4(vv[vi]) * rk) * bf4(gg[vi]);
;             *(u32x2*)(ostg + fr * 144 + (vi * 16 + fq * 4) * 2) = (u32x2){pk2(o[0], o[1]), pk2(o[2], o[3])};
;         }
;         LDS_WAIT();
; #pragma unroll
;         for (int j = 0; j < 2; ++j) {
;             const int tk = (lane >> 3) + 8 * j, c16 = lane & 7;
;             const size_t tg = (size_t)b * SEQ + ck * 64 + tt * 16 + tk;
;             *(u32x4*)(YA + tg * 512 + h * 64 + c16 * 8) = *(const u32x4*)(ostg + tk * 144 + c16 * 16);
;         }
;         LDS_WAIT();
; __device__ __forceinline__ void xcd_barrier(const XcdBarrier& b) {
;     asm volatile("s_waitcnt vmcnt(0)" ::: "memory");
;     __syncthreads();
	v_fmamk_f32 v79, v136, 0xbc800000, v87
	v_fmac_f32_e32 v85, 0xbc800000, v136
	v_lshlrev_b64 v[56:57], 7, v[56:57]
	s_lshl_b32 s0, s0, 4
	v_fmamk_f32 v78, v136, 0xbc800000, v86
	v_fmamk_f32 v84, v136, 0xbc800000, v84
	v_mul_f32_e32 v86, v85, v85
	v_mul_f32_e32 v87, v79, v79
	v_lshl_add_u64 v[56:57], s[22:23], 0, v[56:57]
	s_and_b32 s4, s0, 0x70
	v_fmac_f32_e32 v86, v84, v84
	v_fmac_f32_e32 v87, v78, v78
	v_lshl_add_u64 v[56:57], v[56:57], 0, s[4:5]
	v_add_f32_e32 v86, v86, v87
	s_lshl_b32 s4, s14, 2
	v_add_f32_e32 v86, v86, v137
	v_add_u32_e32 v136, s4, v159
	s_nop 0
	s_nop 0
	v_mov_b32_e32 v87, v86
	s_nop 0
	s_nop 0
	v_permlane32_swap_b32_e32 v86, v87
	global_load_dwordx2 v[114:115], v[40:41], off nt
	v_add_f32_e32 v86, v86, v87
	s_nop 0
	s_nop 0
	s_nop 0
	s_nop 0
	global_load_dwordx2 v[110:111], v[40:41], off offset:2048 nt
	ds_read_b128 v[140:143], v136
	ds_read_b128 v[146:149], v136 offset:2048
	v_mov_b32_e32 v87, v86
	s_nop 1
	v_permlane16_swap_b32_e32 v86, v87
	v_add_f32_e32 v86, v86, v87
	v_fmamk_f32 v86, v86, 0x3c800000, v145
	s_mov_b32 s0, 0x800000
	s_or_b32 s20, s20, s1
	v_cmp_gt_f32_e64 s[0:1], s0, v86
	v_mul_f32_e32 v87, 0x4b800000, v86
	s_or_b64 s[20:21], s[20:21], s[6:7]
	v_cndmask_b32_e64 v86, v86, v87, s[0:1]
	v_rsq_f32_e32 v86, v86
	s_lshl_b64 s[20:21], s[20:21], 7
	v_lshl_add_u64 v[48:49], v[116:117], 0, s[20:21]
	v_lshl_add_u64 v[50:51], v[118:119], 0, s[20:21]
	v_mul_f32_e32 v87, 0x45800000, v86
	v_cndmask_b32_e64 v86, v86, v87, s[0:1]
	v_pk_mul_f32 v[152:153], v[88:89], v[86:87] op_sel_hi:[1,0]
	v_pk_mul_f32 v[88:89], v[150:151], v[86:87] op_sel_hi:[1,0]
	v_lshl_add_u64 v[40:41], v[48:49], 0, v[130:131]
	v_lshl_add_u64 v[48:49], v[48:49], 0, v[132:133]
	v_add_f32_e32 v134, v134, v135
	global_load_dwordx4 v[44:47], v[40:41], off nt
	global_load_dwordx4 v[52:55], v[48:49], off nt
	v_lshl_add_u64 v[40:41], v[50:51], 0, v[130:131]
	v_lshl_add_u64 v[48:49], v[50:51], 0, v[132:133]
	global_load_dwordx4 v[40:43], v[40:41], off nt
	s_ashr_i32 s9, s8, 31
	global_load_dwordx4 v[48:51], v[48:49], off nt
	s_and_b32 s4, s11, 0xfc0
	global_load_dwordx4 v[56:59], v[56:57], off nt
	s_lshl_b64 s[0:1], s[8:9], 12
	s_or_b32 s4, s4, s6
	s_or_b32 s0, s0, s4
	s_lshl_b32 s4, s14, 1
	s_add_i32 s11, s11, s12
	s_nop 0
	s_waitcnt lgkmcnt(0)
	v_pk_fma_f32 v[88:89], v[142:143], v[88:89], v[148:149]
	v_pk_fma_f32 v[140:141], v[140:141], v[152:153], v[146:147]
	s_nop 0
	v_lshlrev_b32_e32 v142, 16, v68
	v_and_b32_e32 v143, 0xffff0000, v68
	v_lshlrev_b32_e32 v68, 16, v69
	v_and_b32_e32 v69, 0xffff0000, v69
	v_pk_fma_f32 v[140:141], v[134:135], v[142:143], v[140:141] op_sel_hi:[0,1,1]
	v_pk_fma_f32 v[68:69], v[134:135], v[68:69], v[88:89] op_sel_hi:[0,1,1]
	s_nop 0
	v_lshlrev_b32_e32 v88, 16, v72
	v_and_b32_e32 v89, 0xffff0000, v72
	v_lshlrev_b32_e32 v72, 16, v73
	v_and_b32_e32 v73, 0xffff0000, v73
	v_pk_mul_f32 v[68:69], v[68:69], v[72:73]
	v_pk_mul_f32 v[72:73], v[140:141], v[88:89]
	ds_read_b128 v[140:143], v136 offset:64
	ds_read_b128 v[146:149], v136 offset:2112
	v_cvt_pk_bf16_f32 v72, v72, v73
	v_cvt_pk_bf16_f32 v73, v68, v69
	v_pk_mul_f32 v[68:69], v[76:77], v[86:87] op_sel_hi:[1,0]
	v_pk_mul_f32 v[76:77], v[90:91], v[86:87] op_sel_hi:[1,0]
	v_lshlrev_b32_e32 v88, 16, v70
	v_and_b32_e32 v89, 0xffff0000, v70
	v_lshlrev_b32_e32 v70, 16, v71
	v_and_b32_e32 v71, 0xffff0000, v71
	s_nop 0
	s_waitcnt lgkmcnt(0)
	v_pk_fma_f32 v[76:77], v[142:143], v[76:77], v[148:149]
	v_pk_fma_f32 v[68:69], v[140:141], v[68:69], v[146:147]
	v_pk_fma_f32 v[70:71], v[134:135], v[70:71], v[76:77] op_sel_hi:[0,1,1]
	v_pk_fma_f32 v[68:69], v[134:135], v[88:89], v[68:69] op_sel_hi:[0,1,1]
	v_lshlrev_b32_e32 v76, 16, v74
	v_and_b32_e32 v77, 0xffff0000, v74
	v_lshlrev_b32_e32 v74, 16, v75
	v_and_b32_e32 v75, 0xffff0000, v75
	v_pk_mul_f32 v[70:71], v[70:71], v[74:75]
	v_pk_mul_f32 v[68:69], v[68:69], v[76:77]
	v_pk_mul_f32 v[76:77], v[80:81], v[86:87] op_sel_hi:[1,0]
	v_cvt_pk_bf16_f32 v68, v68, v69
	v_cvt_pk_bf16_f32 v69, v70, v71
	ds_write2_b64 v144, v[72:73], v[68:69] offset1:4
	ds_read_b128 v[68:71], v136 offset:128
	ds_read_b128 v[72:75], v136 offset:2176
	v_pk_mul_f32 v[80:81], v[82:83], v[86:87] op_sel_hi:[1,0]
	s_nop 0
	s_waitcnt lgkmcnt(0)
	v_pk_fma_f32 v[68:69], v[68:69], v[76:77], v[72:73]
	v_pk_fma_f32 v[70:71], v[70:71], v[80:81], v[74:75]
	v_lshlrev_b32_e32 v72, 16, v60
	v_and_b32_e32 v73, 0xffff0000, v60
	v_lshlrev_b32_e32 v60, 16, v61
	v_and_b32_e32 v61, 0xffff0000, v61
	v_pk_fma_f32 v[68:69], v[134:135], v[72:73], v[68:69] op_sel_hi:[0,1,1]
	v_pk_fma_f32 v[60:61], v[134:135], v[60:61], v[70:71] op_sel_hi:[0,1,1]
	s_nop 0
	v_lshlrev_b32_e32 v70, 16, v64
	v_and_b32_e32 v71, 0xffff0000, v64
	v_lshlrev_b32_e32 v64, 16, v65
	v_and_b32_e32 v65, 0xffff0000, v65
	v_pk_mul_f32 v[60:61], v[60:61], v[64:65]
	v_pk_mul_f32 v[64:65], v[68:69], v[70:71]
	ds_read_b128 v[68:71], v136 offset:192
	ds_read_b128 v[72:75], v136 offset:2240
	v_cvt_pk_bf16_f32 v64, v64, v65
	v_cvt_pk_bf16_f32 v65, v60, v61
	v_pk_mul_f32 v[60:61], v[84:85], v[86:87] op_sel_hi:[1,0]
	v_pk_mul_f32 v[76:77], v[78:79], v[86:87] op_sel_hi:[1,0]
	s_nop 0
	s_waitcnt lgkmcnt(0)
	v_pk_fma_f32 v[60:61], v[68:69], v[60:61], v[72:73]
	v_pk_fma_f32 v[70:71], v[70:71], v[76:77], v[74:75]
	v_lshlrev_b32_e32 v68, 16, v62
	v_and_b32_e32 v69, 0xffff0000, v62
	v_lshlrev_b32_e32 v62, 16, v63
	v_and_b32_e32 v63, 0xffff0000, v63
	v_pk_fma_f32 v[60:61], v[134:135], v[68:69], v[60:61] op_sel_hi:[0,1,1]
	v_pk_fma_f32 v[62:63], v[134:135], v[62:63], v[70:71] op_sel_hi:[0,1,1]
	v_lshlrev_b32_e32 v68, 16, v66
	v_and_b32_e32 v69, 0xffff0000, v66
	v_lshlrev_b32_e32 v66, 16, v67
	v_and_b32_e32 v67, 0xffff0000, v67
	v_pk_mul_f32 v[62:63], v[62:63], v[66:67]
	v_pk_mul_f32 v[60:61], v[60:61], v[68:69]
	v_lshl_add_u64 v[66:67], s[0:1], 0, v[104:105]
	v_cvt_pk_bf16_f32 v60, v60, v61
	v_cvt_pk_bf16_f32 v61, v62, v63
	ds_write2_b64 v144, v[64:65], v[60:61] offset0:8 offset1:12
	s_waitcnt lgkmcnt(0)
	ds_read_b128 v[60:63], v93
	v_lshl_add_u64 v[64:65], v[120:121], 0, s[4:5]
	v_lshlrev_b64 v[66:67], 10, v[66:67]
	v_lshl_add_u64 v[66:67], v[64:65], 0, v[66:67]
	s_nop 0
	s_waitcnt lgkmcnt(0)
	global_store_dwordx4 v[66:67], v[60:63], off
	ds_read_b128 v[60:63], v93 offset:1152
	v_lshl_add_u64 v[66:67], s[0:1], 0, v[106:107]
	v_lshlrev_b64 v[66:67], 10, v[66:67]
	v_lshl_add_u64 v[64:65], v[64:65], 0, v[66:67]
	s_mov_b32 s0, s13
	s_nop 0
	s_waitcnt lgkmcnt(0)
	global_store_dwordx4 v[64:65], v[60:63], off
	s_waitcnt lgkmcnt(0)
	s_cbranch_vccnz .LBB0_577
.LBB0_578:
	s_setprio 0
	s_waitcnt vmcnt(0)
	s_barrier
	s_and_saveexec_b64 s[0:1], s[66:67]
	s_mov_b64 s[70:71], s[76:77]
	s_cbranch_execz .LBB0_630
	s_add_i32 s2, 0, 0x23ff0
	v_mov_b32_e32 v0, s2
	s_waitcnt vmcnt(0) expcnt(0) lgkmcnt(0)
	ds_read_b32 v2, v0
	s_add_i32 s2, 0, 0x23ff4
	v_mov_b32_e32 v0, s2
	ds_read_b32 v0, v0
	s_waitcnt lgkmcnt(1)
	v_cmp_ne_u32_e32 vcc, 0, v2
	s_cbranch_vccnz .LBB0_594
	s_mov_b32 s2, 1
	v_mov_b32_e32 v16, 0
	s_branch .LBB0_582
